# attention loop: the s_nop 1 in front of v_permlane32_swap removed (the preceding PV MFMA and its ds_read refill supply the two wait states), shortening the max->branch chain
# baseline (speedup 1.0000x reference)
; #define LAS __attribute__((address_space(3)))
; #define MFMA32(a, b, c) __builtin_amdgcn_mfma_f32_32x32x16_bf16((a), (b), (c), 0, 0, 0)
; __device__ __forceinline__ void diff_unit_lds(LAS unsigned char* lds, const bf16* Qd, const bf16* Kd, const bf16* VdT, bf16* MIX, const float* ghead, float lam, int head, int u, int wave, int lane) {
;     ...
;             for (int ds = 0; ds < 4; ++ds) S0 = MFMA32(*(const LAS bf16x8*)(st + koff + (((2 * ds + h) ^ kx) << 4)), qf[ds], S0);
;             if (!part) {
; #pragma unroll
;                 for (int ds = 0; ds < 4; ++ds) S1 = MFMA32(*(const LAS bf16x8*)(st + koff + 4096 + (((2 * ds + h) ^ kx) << 4)), qf[ds], S1);
;             }
;             float tmax = S0[0];
; #pragma unroll
;             for (int i = 1; i < 16; ++i) tmax = fmaxf(tmax, S0[i]);
;             if (masked) tmax = -1e30f;
;             if (!part) {
; #pragma unroll
;                 for (int i = 0; i < 16; ++i) tmax = fmaxf(tmax, S1[i]);
;             }
;             tmax = fmaxf(tmax, xhalf(tmax, h));
;             if (T == 0 || __any(tmax > 8.0f)) {
.Lq_prio_done:
.Lq_even_top:
	s_cmp_eq_u32 s94, s92
	s_cbranch_scc1 .Lq_last
	s_lshr_b32 s0, s94, 1
	s_and_b32 s0, s0, 3
	s_lshl_b32 s95, s0, 15
	ds_read_b128 v[164:167], v203 offset:4096
	ds_read_b128 v[168:171], v204 offset:4096
	ds_read_b128 v[172:175], v192 offset:4096
	ds_read_b128 v[176:179], v193 offset:4096
	v_add_u32_e32 v208, s95, v133
	v_add_u32_e32 v213, s95, v205
	s_waitcnt lgkmcnt(4)
	v_mfma_f32_32x32x16_bf16 v[50:65], v[220:223], v[82:85], v[50:65]
	ds_read_b128 v[220:223], v208 offset:16384
	v_max3_f32 v1, v98, v99, v100
	v_max3_f32 v1, v1, v101, v102
	v_max3_f32 v1, v1, v103, v104
	v_max3_f32 v1, v1, v105, v106
	v_max3_f32 v1, v1, v107, v108
	v_mfma_f32_32x32x16_bf16 v[34:49], v[226:229], v[82:85], v[34:49]
	ds_read_b128 v[226:229], v208 offset:20480
	v_max3_f32 v1, v1, v109, v110
	v_max3_f32 v1, v1, v111, v112
	v_max_f32_e32 v224, v1, v113
	v_max_f32_e32 v225, v1, v113
	v_mfma_f32_32x32x16_bf16 v[18:33], v[230:233], v[82:85], v[18:33]
	ds_read_b128 v[230:233], v208 offset:24576
	v_permlane32_swap_b32_e32 v224, v225
	v_max_f32_e32 v1, v224, v225
	v_cmp_lt_f32_e32 vcc, s96, v1
	s_cbranch_vccnz .Lq_re_e

; #define LAS __attribute__((address_space(3)))
; #define MFMA32(a, b, c) __builtin_amdgcn_mfma_f32_32x32x16_bf16((a), (b), (c), 0, 0, 0)
; #define DIFF_ISSUE(T_) do { const unsigned sb_ = lbase + (unsigned)((T_) & 3) * 32768u; const bf16* k_ = gk + (size_t)(T_) * (64 * 512); const bf16* v_ = gv + (size_t)(T_) * 64; \
;         glds16(k_, sb_); glds16(k_ + 64, sb_ + 8192u); glds16(v_, sb_ + 16384u); glds16(v_ + (size_t)64 * VPITCH, sb_ + 24576u); } while (0)
; __device__ __forceinline__ void diff_unit_lds(LAS unsigned char* lds, const bf16* Qd, const bf16* Kd, const bf16* VdT, bf16* MIX, const float* ghead, float lam, int head, int u, int wave, int lane) {
;     ...
;         if ((T & 1) == 0) {
;             asm volatile("s_waitcnt vmcnt(0) lgkmcnt(0)\n\ts_barrier" ::: "memory");
;             if (T + 2 < nT) DIFF_ISSUE(T + 2);
;             if (T + 3 < nT) DIFF_ISSUE(T + 3);
;         }
;         if (T <= Tlast) {
;             const bool part = (T == Tlast);
;             const bool masked = part && (h == 1);
;             f32x16 S0 = NEGM, S1 = NEGM;
; #pragma unroll
;             for (int ds = 0; ds < 4; ++ds) S0 = MFMA32(*(const LAS bf16x8*)(st + koff + (((2 * ds + h) ^ kx) << 4)), qf[ds], S0);
;             if (!part) {
; #pragma unroll
;                 for (int ds = 0; ds < 4; ++ds) S1 = MFMA32(*(const LAS bf16x8*)(st + koff + 4096 + (((2 * ds + h) ^ kx) << 4)), qf[ds], S1);
;             }
;             float tmax = S0[0];
; #pragma unroll
;             for (int i = 1; i < 16; ++i) tmax = fmaxf(tmax, S0[i]);
;             if (masked) tmax = -1e30f;
;             if (!part) {
; #pragma unroll
;                 for (int i = 0; i < 16; ++i) tmax = fmaxf(tmax, S1[i]);
;             }
;             tmax = fmaxf(tmax, xhalf(tmax, h));
;             if (T == 0 || __any(tmax > 8.0f)) {
.Lq_wd:
	s_barrier
	s_cmp_lt_u32 s57, 2
	s_cbranch_scc1 .Lq_odd_nodma
	s_cmp_gt_u32 s57, s93
	s_cbranch_scc1 .Lq_odd_nodma
	s_add_i32 s6, s57, 2
	s_and_b32 s0, s6, 3
	s_lshl_b32 s0, s0, 15
	s_add_i32 s1, s0, s33
	s_mov_b32 s7, m0
	s_lshr_b32 s0, s94, 1
	s_and_b32 s0, s0, 3
	s_lshl_b32 s95, s0, 15
	s_and_b32 s0, s57, 3
	s_lshl_b32 s58, s0, 15
	v_add_u32_e32 v203, s58, v209
	ds_read_b128 v[164:167], v203
	v_add_u32_e32 v204, s58, v210
	ds_read_b128 v[168:171], v204
	v_add_u32_e32 v192, s58, v211
	ds_read_b128 v[172:175], v192
	v_add_u32_e32 v193, s58, v212
	ds_read_b128 v[176:179], v193
	v_add_u32_e32 v208, s95, v206
	v_add_u32_e32 v213, s95, v207
	s_waitcnt lgkmcnt(4)
	v_mfma_f32_32x32x16_bf16 v[50:65], v[220:223], v[98:101], v[50:65]
	ds_read_b128 v[220:223], v208 offset:16384
	s_lshl_b32 s8, s6, 16
	s_mov_b32 s9, 0
	s_mov_b32 m0, s1
	v_lshl_add_u64 v[180:181], v[158:159], 0, s[8:9]
	global_load_lds_dwordx4 v[180:181], off
	v_max3_f32 v1, v82, v83, v84
	v_max3_f32 v1, v1, v85, v86
	v_max3_f32 v1, v1, v87, v88
	v_max3_f32 v1, v1, v89, v90
	v_max3_f32 v1, v1, v91, v92
	v_mfma_f32_32x32x16_bf16 v[34:49], v[226:229], v[98:101], v[34:49]
	ds_read_b128 v[226:229], v208 offset:20480
	s_add_i32 s8, s8, 0x80
	s_add_i32 s0, s1, 0x2000
	s_mov_b32 m0, s0
	v_lshl_add_u64 v[182:183], v[158:159], 0, s[8:9]
	global_load_lds_dwordx4 v[182:183], off
	v_max3_f32 v1, v1, v93, v94
	v_max3_f32 v1, v1, v95, v96
	v_max_f32_e32 v224, v1, v97
	v_max_f32_e32 v225, v1, v97
	v_mfma_f32_32x32x16_bf16 v[18:33], v[230:233], v[98:101], v[18:33]
	ds_read_b128 v[230:233], v208 offset:24576
	s_lshl_b32 s8, s6, 7
	s_add_i32 s0, s1, 0x4000
	s_mov_b32 m0, s0
	v_lshl_add_u64 v[184:185], v[156:157], 0, s[8:9]
	global_load_lds_dwordx4 v[184:185], off
	v_permlane32_swap_b32_e32 v224, v225
	v_max_f32_e32 v1, v224, v225
	v_cmp_lt_f32_e32 vcc, s96, v1
	s_cbranch_vccnz .Lq_re_od

; #define LAS __attribute__((address_space(3)))
; #define MFMA32(a, b, c) __builtin_amdgcn_mfma_f32_32x32x16_bf16((a), (b), (c), 0, 0, 0)
; __device__ __forceinline__ void diff_unit_lds(LAS unsigned char* lds, const bf16* Qd, const bf16* Kd, const bf16* VdT, bf16* MIX, const float* ghead, float lam, int head, int u, int wave, int lane) {
;     ...
;             for (int ds = 0; ds < 4; ++ds) S0 = MFMA32(*(const LAS bf16x8*)(st + koff + (((2 * ds + h) ^ kx) << 4)), qf[ds], S0);
;             if (!part) {
; #pragma unroll
;                 for (int ds = 0; ds < 4; ++ds) S1 = MFMA32(*(const LAS bf16x8*)(st + koff + 4096 + (((2 * ds + h) ^ kx) << 4)), qf[ds], S1);
;             }
;             float tmax = S0[0];
; #pragma unroll
;             for (int i = 1; i < 16; ++i) tmax = fmaxf(tmax, S0[i]);
;             if (masked) tmax = -1e30f;
;             if (!part) {
; #pragma unroll
;                 for (int i = 0; i < 16; ++i) tmax = fmaxf(tmax, S1[i]);
;             }
;             tmax = fmaxf(tmax, xhalf(tmax, h));
;             if (T == 0 || __any(tmax > 8.0f)) {
.Lq_odd_nodma:
	s_lshr_b32 s0, s94, 1
	s_and_b32 s0, s0, 3
	s_lshl_b32 s95, s0, 15
	s_and_b32 s0, s57, 3
	s_lshl_b32 s58, s0, 15
	v_add_u32_e32 v203, s58, v209
	ds_read_b128 v[164:167], v203
	v_add_u32_e32 v204, s58, v210
	ds_read_b128 v[168:171], v204
	v_add_u32_e32 v192, s58, v211
	ds_read_b128 v[172:175], v192
	v_add_u32_e32 v193, s58, v212
	ds_read_b128 v[176:179], v193
	v_add_u32_e32 v208, s95, v206
	v_add_u32_e32 v213, s95, v207
	s_waitcnt lgkmcnt(4)
	v_mfma_f32_32x32x16_bf16 v[50:65], v[220:223], v[98:101], v[50:65]
	ds_read_b128 v[220:223], v208 offset:16384
	v_max3_f32 v1, v82, v83, v84
	v_max3_f32 v1, v1, v85, v86
	v_max3_f32 v1, v1, v87, v88
	v_max3_f32 v1, v1, v89, v90
	v_max3_f32 v1, v1, v91, v92
	v_mfma_f32_32x32x16_bf16 v[34:49], v[226:229], v[98:101], v[34:49]
	ds_read_b128 v[226:229], v208 offset:20480
	v_max3_f32 v1, v1, v93, v94
	v_max3_f32 v1, v1, v95, v96
	v_max_f32_e32 v224, v1, v97
	v_max_f32_e32 v225, v1, v97
	v_mfma_f32_32x32x16_bf16 v[18:33], v[230:233], v[98:101], v[18:33]
	ds_read_b128 v[230:233], v208 offset:24576
	v_permlane32_swap_b32_e32 v224, v225
	v_max_f32_e32 v1, v224, v225
	v_cmp_lt_f32_e32 vcc, s96, v1
	s_cbranch_vccnz .Lq_re_on

; __device__ __forceinline__ void diff_unit_lds(LAS unsigned char* lds, const bf16* Qd, const bf16* Kd, const bf16* VdT, bf16* MIX, const float* ghead, float lam, int head, int u, int wave, int lane) {
;     ...
;             float tmax = S0[0];
; #pragma unroll
;             for (int i = 1; i < 16; ++i) tmax = fmaxf(tmax, S0[i]);
;             if (masked) tmax = -1e30f;
;             if (!part) {
; #pragma unroll
;                 for (int i = 0; i < 16; ++i) tmax = fmaxf(tmax, S1[i]);
;             }
;             tmax = fmaxf(tmax, xhalf(tmax, h));
;             if (T == 0 || __any(tmax > 8.0f)) {
.Lq_last:
	s_lshr_b32 s0, s94, 1
	s_and_b32 s0, s0, 3
	s_lshl_b32 s95, s0, 15
	v_add_u32_e32 v208, s95, v133
	v_add_u32_e32 v213, s95, v205
	s_waitcnt lgkmcnt(0)
	v_mfma_f32_32x32x16_bf16 v[50:65], v[220:223], v[82:85], v[50:65]
	ds_read_b128 v[220:223], v208 offset:16384
	v_max3_f32 v1, v98, v99, v100
	v_max3_f32 v1, v1, v101, v102
	v_max3_f32 v1, v1, v103, v104
	v_max3_f32 v1, v1, v105, v106
	v_max3_f32 v1, v1, v107, v108
	v_mfma_f32_32x32x16_bf16 v[34:49], v[226:229], v[82:85], v[34:49]
	ds_read_b128 v[226:229], v208 offset:20480
	v_max3_f32 v1, v1, v109, v110
	v_max3_f32 v1, v1, v111, v112
	v_max_f32_e32 v1, v1, v113
	v_cndmask_b32_e64 v1, v1, v217, s[2:3]
	v_mov_b32_e32 v224, v1
	v_mov_b32_e32 v225, v1
	v_mfma_f32_32x32x16_bf16 v[18:33], v[230:233], v[82:85], v[18:33]
	ds_read_b128 v[230:233], v208 offset:24576
	v_permlane32_swap_b32_e32 v224, v225
	v_max_f32_e32 v1, v224, v225
	v_cmp_lt_f32_e32 vcc, s96, v1
	s_cbranch_vccnz .Lq_re_m
